# merge phase: one static priority raise for the second wave half (waves 4-7)
# baseline (speedup 1.0000x reference)
.LBB0_233:
	s_andn2_b64 vcc, exec, s[2:3]
	s_cbranch_vccnz .LBB0_277
	s_mov_b64 s[22:23], s[96:97]
	v_mov_b32_e32 v2, v1
	s_load_dwordx2 s[2:3], s[22:23], 0xf8
	s_load_dwordx2 s[30:31], s[22:23], 0xb0
	s_load_dword s39, s[72:73], 0x10
	s_mul_i32 s38, s28, 0x3000
	s_mul_hi_i32 s24, s28, 0x3000
	s_waitcnt lgkmcnt(0)
	s_add_u32 s33, s2, 0x6400000
	s_addc_u32 s46, s3, 0
	s_add_u32 s47, s2, 0x2400000
	s_addc_u32 s48, s3, 0
	s_add_u32 s22, s2, 0x15c00000
	s_addc_u32 s23, s3, 0
	s_add_u32 s30, s30, s38
	s_addc_u32 s31, s31, s24
	s_lshr_b32 s24, s39, 16
	s_cmp_lg_u32 s24, 0
	s_cselect_b64 s[38:39], -1, 0
	s_cmp_lg_u64 s[38:39], 0
	s_addc_u32 s24, s74, 0
	v_and_b32_e32 v3, 64, v2
	s_lshr_b32 s50, s24, 3
	v_lshrrev_b32_e32 v4, 1, v2
	v_and_b32_e32 v2, 15, v2
	s_mov_b32 s24, 0x3fffc0
	v_and_or_b32 v35, v4, 24, v3
	s_add_u32 s51, s2, 0xe40000
	v_and_or_b32 v2, v4, s24, v2
	s_mov_b32 s49, 0
	s_addc_u32 s52, s3, 0
	v_lshl_or_b32 v206, v2, 10, v35
	v_cmp_lt_u32_e32 vcc, 0xff, v1
	s_nop 4
	s_cbranch_vccz .Lmp_skip
	s_setprio 1
.Lmp_skip:
	s_branch .LBB0_237
.LBB0_235:
	s_add_i32 s49, s49, 1
	s_mov_b64 s[40:41], 0

.LBB0_744:
	s_setprio 0
	s_waitcnt vmcnt(0)
	s_waitcnt lgkmcnt(0)
	s_barrier
	s_mov_b64 s[0:1], exec
	v_readlane_b32 s2, v245, 0
	v_readlane_b32 s3, v245, 1
	s_and_b64 s[2:3], s[0:1], s[2:3]
	s_mov_b64 exec, s[2:3]
	s_cbranch_execz .LBB0_19
	v_readlane_b32 s2, v244, 6
	s_waitcnt vmcnt(0) expcnt(0) lgkmcnt(0)
	s_nop 0
	v_mov_b32_e32 v2, s2
	ds_read_b32 v4, v2
	v_readlane_b32 s2, v244, 7
	s_waitcnt lgkmcnt(0)
	v_cmp_ne_u32_e32 vcc, 0, v4
	v_mov_b32_e32 v2, s2
	ds_read_b32 v2, v2
	s_cbranch_vccnz .LBB0_760
	s_mov_b32 s22, 1
	s_branch .LBB0_748
